# layer-0 deferred weight transposes taken only by blocks 256..383 (the blocks that skip attention), other workers start attention immediately
# speedup vs baseline: 1.0033x; 1.0033x over previous
; __device__ __forceinline__ void phase_mixers(const Params& p, int l, unsigned char* smem) {
;     ...
;     if (l == 0) {
;       for (;;) {
;         __syncthreads();
;         if (tid == 0) *tsl = (int)atomicAdd(&p.ctrs[2], 1u);
;         __syncthreads();
;         const int t = *tsl;
;         if (t >= 1440) break;
;         deferred_transpose(p, t, smem);
;       }
;     }
.LBB0_549:
	s_barrier
	s_and_saveexec_b64 s[44:45], s[42:43]
	s_cbranch_execz .LBB0_553
	s_mov_b64 s[48:49], exec
	v_mbcnt_lo_u32_b32 v0, s48, 0
	v_mbcnt_hi_u32_b32 v0, s49, v0
	v_cmp_eq_u32_e32 vcc, 0, v0
	s_and_saveexec_b64 s[46:47], vcc
	s_cbranch_execz .LBB0_552
	s_bcnt1_i32_b64 s28, s[48:49]
	v_readlane_b32 s0, v252, 0
	v_mov_b32_e32 v1, s28
	v_readlane_b32 s28, v255, 38
	s_nop 0
	s_sub_i32 s28, s28, 256
	s_cmp_lt_u32 s28, 128
	v_readlane_b32 s14, v252, 14
	v_readlane_b32 s15, v252, 15
	v_readlane_b32 s1, v252, 1
	v_readlane_b32 s2, v252, 2
	v_readlane_b32 s3, v252, 3
	v_readlane_b32 s4, v252, 4
	v_readlane_b32 s5, v252, 5
	s_cbranch_scc0 .Ltr_skip
	global_atomic_add v1, v164, v1, s[14:15] offset:8 sc0
	s_branch .Ltr_join

; __device__ __forceinline__ void phase_mixers(const Params& p, int l, unsigned char* smem) {
;     ...
;     if (l == 0) {
;       for (;;) {
;         __syncthreads();
;         if (tid == 0) *tsl = (int)atomicAdd(&p.ctrs[2], 1u);
;         __syncthreads();
;         const int t = *tsl;
;         if (t >= 1440) break;
;         deferred_transpose(p, t, smem);
;       }
;     }
.Ltr_join:
	v_readlane_b32 s6, v252, 6
	v_readlane_b32 s7, v252, 7
	v_readlane_b32 s8, v252, 8
	v_readlane_b32 s9, v252, 9
	v_readlane_b32 s10, v252, 10
	v_readlane_b32 s11, v252, 11
	v_readlane_b32 s12, v252, 12
	v_readlane_b32 s13, v252, 13
